# attn: z-gate loads hoisted to item start, sink via scalar load, no vmcnt0 at item barrier
# speedup vs baseline: 1.0076x; 1.0076x over previous
.LBB0_1036:
	s_waitcnt vmcnt(0)
	ds_bpermute_b32 v6, v195, v149
	v_lshlrev_b64 v[0:1], 11, v[156:157]
	v_lshl_add_u64 v[0:1], s[84:85], 0, v[0:1]
	s_lshl_b32 s80, s89, 7
	v_lshlrev_b32_e32 v72, 1, v78
	s_waitcnt lgkmcnt(0)
	v_add_f32_e32 v10, v149, v6
	ds_bpermute_b32 v11, v196, v10
	v_lshl_add_u64 v[6:7], v[0:1], 0, s[80:81]
	v_lshl_add_u64 v[8:9], v[6:7], 0, v[72:73]
	s_waitcnt lgkmcnt(0)
	v_add_f32_e32 v0, v10, v11
	v_div_scale_f32 v1, s[0:1], v0, v0, 1.0
	v_div_scale_f32 v13, vcc, 1.0, v0, 1.0
	v_rcp_f32_e32 v12, v1
	s_nop 1
	v_fma_f32 v14, -v1, v12, 1.0
	v_fmac_f32_e32 v12, v14, v12
	v_mul_f32_e32 v14, v13, v12
	v_fma_f32 v15, -v1, v14, v13
	v_fmac_f32_e32 v14, v15, v12
	v_fma_f32 v1, -v1, v14, v13
	v_div_fmas_f32 v1, v1, v12, v14
	v_div_fixup_f32 v0, v1, v0, 1.0
	v_readlane_b32 s0, v240, 11
	s_add_i32 s73, s73, s0
	s_cmpk_lt_i32 s73, 0x1080
	v_readlane_b32 s1, v240, 12
	v_lshlrev_b32_e32 v12, 16, v242
	v_and_b32_e32 v13, 0xffff0000, v242
	v_lshlrev_b32_e32 v4, 16, v243
	v_and_b32_e32 v5, 0xffff0000, v243
	v_mul_f32_e32 v1, 0xbfb8aa3b, v12
	v_mul_f32_e32 v14, 0xbfb8aa3b, v13
	v_mul_f32_e32 v15, 0xbfb8aa3b, v4
	v_mul_f32_e32 v16, 0xbfb8aa3b, v5
	v_exp_f32_e32 v1, v1
	v_exp_f32_e32 v14, v14
	v_exp_f32_e32 v15, v15
	v_exp_f32_e32 v16, v16
	v_add_f32_e32 v1, 1.0, v1
	v_add_f32_e32 v17, 1.0, v14
	v_add_f32_e32 v18, 1.0, v15
	v_add_f32_e32 v19, 1.0, v16
	v_rcp_f32_e32 v14, v1
	v_rcp_f32_e32 v15, v17
	v_rcp_f32_e32 v16, v18
	v_rcp_f32_e32 v17, v19
	v_pk_mul_f32 v[18:19], v[36:37], v[0:1] op_sel_hi:[1,0]
	v_pk_mul_f32 v[20:21], v[38:39], v[0:1] op_sel_hi:[1,0]
	v_pk_mul_f32 v[12:13], v[14:15], v[12:13]
	v_pk_mul_f32 v[4:5], v[16:17], v[4:5]
	v_pk_mul_f32 v[12:13], v[18:19], v[12:13]
	v_pk_mul_f32 v[4:5], v[20:21], v[4:5]
	v_cvt_pk_bf16_f32 v12, v12, v13
	v_cvt_pk_bf16_f32 v13, v4, v5
	global_store_dwordx2 v[8:9], v[12:13], off
	v_lshlrev_b32_e32 v12, 16, v244
	v_and_b32_e32 v13, 0xffff0000, v244
	v_lshlrev_b32_e32 v4, 16, v245
	v_and_b32_e32 v5, 0xffff0000, v245
	v_mul_f32_e32 v1, 0xbfb8aa3b, v12
	v_mul_f32_e32 v14, 0xbfb8aa3b, v13
	v_mul_f32_e32 v15, 0xbfb8aa3b, v4
	v_mul_f32_e32 v16, 0xbfb8aa3b, v5
	v_exp_f32_e32 v1, v1
	v_exp_f32_e32 v14, v14
	v_exp_f32_e32 v15, v15
	v_exp_f32_e32 v16, v16
	v_add_f32_e32 v1, 1.0, v1
	v_add_f32_e32 v17, 1.0, v14
	v_add_f32_e32 v18, 1.0, v15
	v_add_f32_e32 v19, 1.0, v16
	v_rcp_f32_e32 v14, v1
	v_rcp_f32_e32 v15, v17
	v_rcp_f32_e32 v16, v18
	v_rcp_f32_e32 v17, v19
	v_pk_mul_f32 v[18:19], v[32:33], v[0:1] op_sel_hi:[1,0]
	v_pk_mul_f32 v[20:21], v[34:35], v[0:1] op_sel_hi:[1,0]
	v_pk_mul_f32 v[12:13], v[14:15], v[12:13]
	v_pk_mul_f32 v[4:5], v[16:17], v[4:5]
	v_pk_mul_f32 v[12:13], v[18:19], v[12:13]
	v_pk_mul_f32 v[4:5], v[20:21], v[4:5]
	v_cvt_pk_bf16_f32 v12, v12, v13
	v_cvt_pk_bf16_f32 v13, v4, v5
	global_store_dwordx2 v[8:9], v[12:13], off offset:32
	v_lshlrev_b32_e32 v12, 16, v246
	v_and_b32_e32 v13, 0xffff0000, v246
	v_lshlrev_b32_e32 v4, 16, v247
	v_and_b32_e32 v5, 0xffff0000, v247
	v_mul_f32_e32 v1, 0xbfb8aa3b, v12
	v_mul_f32_e32 v14, 0xbfb8aa3b, v13
	v_mul_f32_e32 v15, 0xbfb8aa3b, v4
	v_mul_f32_e32 v16, 0xbfb8aa3b, v5
	v_exp_f32_e32 v1, v1
	v_exp_f32_e32 v14, v14
	v_exp_f32_e32 v15, v15
	v_exp_f32_e32 v16, v16
	v_add_f32_e32 v1, 1.0, v1
	v_add_f32_e32 v17, 1.0, v14
	v_add_f32_e32 v18, 1.0, v15
	v_add_f32_e32 v19, 1.0, v16
	v_rcp_f32_e32 v14, v1
	v_rcp_f32_e32 v15, v17
	v_rcp_f32_e32 v16, v18
	v_rcp_f32_e32 v17, v19
	v_pk_mul_f32 v[18:19], v[28:29], v[0:1] op_sel_hi:[1,0]
	v_pk_mul_f32 v[20:21], v[30:31], v[0:1] op_sel_hi:[1,0]
	v_pk_mul_f32 v[12:13], v[14:15], v[12:13]
	v_pk_mul_f32 v[4:5], v[16:17], v[4:5]
	v_pk_mul_f32 v[12:13], v[18:19], v[12:13]
	v_pk_mul_f32 v[4:5], v[20:21], v[4:5]
	v_cvt_pk_bf16_f32 v12, v12, v13
	v_cvt_pk_bf16_f32 v13, v4, v5
	global_store_dwordx2 v[8:9], v[12:13], off offset:64
	v_lshlrev_b32_e32 v12, 16, v248
	v_and_b32_e32 v13, 0xffff0000, v248
	v_lshlrev_b32_e32 v4, 16, v249
	v_and_b32_e32 v5, 0xffff0000, v249
	v_mul_f32_e32 v1, 0xbfb8aa3b, v12
	v_mul_f32_e32 v14, 0xbfb8aa3b, v13
	v_mul_f32_e32 v15, 0xbfb8aa3b, v4
	v_mul_f32_e32 v16, 0xbfb8aa3b, v5
	v_exp_f32_e32 v1, v1
	v_exp_f32_e32 v14, v14
	v_exp_f32_e32 v15, v15
	v_exp_f32_e32 v16, v16
	v_add_f32_e32 v1, 1.0, v1
	v_add_f32_e32 v17, 1.0, v14
	v_add_f32_e32 v18, 1.0, v15
	v_add_f32_e32 v19, 1.0, v16
	v_rcp_f32_e32 v14, v1
	v_rcp_f32_e32 v15, v17
	v_rcp_f32_e32 v16, v18
	v_rcp_f32_e32 v17, v19
	v_pk_mul_f32 v[18:19], v[24:25], v[0:1] op_sel_hi:[1,0]
	v_pk_mul_f32 v[20:21], v[26:27], v[0:1] op_sel_hi:[1,0]
	v_pk_mul_f32 v[12:13], v[14:15], v[12:13]
	v_pk_mul_f32 v[4:5], v[16:17], v[4:5]
	v_pk_mul_f32 v[12:13], v[18:19], v[12:13]
	v_pk_mul_f32 v[4:5], v[20:21], v[4:5]
	v_cvt_pk_bf16_f32 v12, v12, v13
	v_cvt_pk_bf16_f32 v13, v4, v5
	global_store_dwordx2 v[8:9], v[12:13], off offset:96
	s_cbranch_scc0 .LBB0_1190

.LBB0_1041:
	s_and_b32 s89, s10, 15
	s_lshl_b32 s4, s89, 2
	s_load_dword s98, s[76:77], s4
	v_add_u32_e32 v156, s18, v77
	s_bfe_u32 s51, s10, 0x20002
	v_ashrrev_i32_e32 v157, 31, v156
	s_add_u32 s100, s78, 0xad20c00
	s_addc_u32 s101, s79, 0
	v_mov_b64_e32 v[250:251], s[100:101]
	s_lshl_b32 s80, s89, 7
	v_mad_i64_i32 v[250:251], vcc, v156, s66, v[250:251]
	v_lshlrev_b32_e32 v252, 1, v78
	v_mov_b32_e32 v253, 0
	v_lshl_add_u64 v[250:251], v[250:251], 0, s[80:81]
	v_lshl_add_u64 v[250:251], v[250:251], 0, v[252:253]
	global_load_dwordx2 v[242:243], v[250:251], off
	global_load_dwordx2 v[244:245], v[250:251], off offset:32
	global_load_dwordx2 v[246:247], v[250:251], off offset:64
	global_load_dwordx2 v[248:249], v[250:251], off offset:96
	s_andn2_b64 vcc, exec, s[0:1]
	s_mov_b64 s[48:49], -1
	s_waitcnt lgkmcnt(0)
	s_barrier
	v_mov_b32_e32 v151, s98
	v_mul_f32_e32 v151, 0x3fb8aa3b, v151
	s_cbranch_vccnz .LBB0_1112
	s_cmp_gt_i32 s50, 62
	s_cbranch_scc1 .LBB0_1112
	s_cmp_eq_u32 s50, 0
	s_cselect_b64 s[48:49], -1, 0
	s_cmp_lg_u32 s50, 0
	s_cbranch_scc0 .LBB0_1112
	s_lshl_b32 s10, s11, 13
	s_lshl_b32 s4, s50, 7
	s_or_b32 s26, s10, s4
	v_add_u32_e32 v0, s26, v89
	v_mov_b64_e32 v[32:33], s[82:83]
	v_mad_i64_i32 v[0:1], s[4:5], v0, s66, v[32:33]
	s_lshl_b32 s80, s51, 7
	v_lshl_add_u64 v[0:1], v[0:1], 0, s[80:81]
	v_lshlrev_b32_e32 v72, 1, v74
	v_lshl_add_u64 v[24:25], v[0:1], 0, v[72:73]
	v_add_u32_e32 v0, s26, v91
	v_mad_i64_i32 v[0:1], s[4:5], v0, s66, v[32:33]
	v_lshl_add_u64 v[0:1], v[0:1], 0, s[80:81]
	v_lshl_add_u64 v[8:9], v[0:1], 0, v[72:73]
	v_add_co_u32_e32 v12, vcc, s67, v8
	global_load_dwordx4 v[0:3], v[8:9], off offset:2048
	global_load_dwordx4 v[4:7], v[8:9], off offset:2560
	v_addc_co_u32_e32 v13, vcc, 0, v9, vcc
	v_add_co_u32_e32 v28, vcc, s67, v24
	global_load_dwordx4 v[8:11], v[12:13], off offset:2048
	s_nop 0
	global_load_dwordx4 v[12:15], v[12:13], off offset:2560
	s_nop 0
	global_load_dwordx4 v[16:19], v[24:25], off offset:2048
	global_load_dwordx4 v[20:23], v[24:25], off offset:2560
	v_addc_co_u32_e32 v29, vcc, 0, v25, vcc
	global_load_dwordx4 v[24:27], v[28:29], off offset:2048
	s_nop 0
	global_load_dwordx4 v[28:31], v[28:29], off offset:2560
	s_lshl_b32 s4, s89, 7
	s_mov_b32 s5, s81
	v_mad_i64_i32 v[32:33], s[18:19], v156, s66, v[32:33]
	v_lshlrev_b32_e32 v34, 1, v76
	v_mov_b32_e32 v35, v73
	v_lshl_add_u64 v[32:33], v[32:33], 0, s[4:5]
	v_lshl_add_u64 v[36:37], v[32:33], 0, v[34:35]
	global_load_dwordx4 v[32:35], v[36:37], off
	s_nop 0
	global_load_dwordx4 v[36:39], v[36:37], off offset:64
	v_mov_b64_e32 v[40:41], s[78:79]
	v_or_b32_e32 v42, s26, v87
	v_mad_i64_i32 v[40:41], s[4:5], v42, s66, v[40:41]
	v_lshl_add_u64 v[40:41], v[40:41], 0, s[80:81]
	s_mov_b32 s18, 0xad20000
	v_lshl_add_u64 v[40:41], v[40:41], 0, v[72:73]
	v_add_co_u32_e32 v44, vcc, s18, v40
	s_mov_b32 s19, 0xad70000
	s_nop 0
	v_addc_co_u32_e32 v45, vcc, 0, v41, vcc
	v_lshl_add_u64 v[42:43], v[40:41], 0, s[86:87]
	v_add_co_u32_e32 v40, vcc, s19, v40
	v_mov_b32_e32 v58, 0
	s_nop 0
	v_addc_co_u32_e32 v41, vcc, 0, v41, vcc
	v_mov_b32_e32 v68, 0
	v_mov_b32_e32 v69, 0
	v_mov_b32_e32 v70, 0
	v_mov_b32_e32 v71, 0
	s_waitcnt vmcnt(9)
	ds_write_b128 v158, v[0:3]
	s_waitcnt vmcnt(8)
	ds_write_b128 v158, v[4:7] offset:18432
	s_waitcnt vmcnt(5)
	ds_write_b128 v158, v[16:19] offset:36864
	s_waitcnt vmcnt(4)
	ds_write_b128 v158, v[20:23] offset:55296
	ds_write_b128 v158, v[8:11] offset:9216
	ds_write_b128 v158, v[12:15] offset:27648
	s_waitcnt vmcnt(3)
	ds_write_b128 v158, v[24:27] offset:46080
	s_waitcnt vmcnt(2)
	ds_write_b128 v158, v[28:31] offset:64512
	s_waitcnt lgkmcnt(0)
	s_barrier
	global_load_dwordx4 v[0:3], v[44:45], off offset:2048
	global_load_dwordx4 v[4:7], v[42:43], off offset:512
	global_load_dwordx4 v[8:11], v[40:41], off offset:2048
	global_load_dwordx4 v[12:15], v[40:41], off offset:2560
	s_waitcnt vmcnt(5)
	v_lshlrev_b32_e32 v16, 16, v32
	s_waitcnt vmcnt(4)
	v_lshlrev_b32_e32 v18, 16, v36
	v_and_b32_e32 v19, 0xffff0000, v36
	v_pk_mul_f32 v[18:19], v[18:19], s[88:89] op_sel_hi:[1,0]
	v_and_b32_e32 v17, 0xffff0000, v32
	v_cvt_pk_bf16_f32 v20, v18, v19
	v_lshlrev_b32_e32 v18, 16, v33
	v_and_b32_e32 v19, 0xffff0000, v33
	v_pk_mul_f32 v[16:17], v[16:17], s[88:89] op_sel_hi:[1,0]
	v_pk_mul_f32 v[18:19], v[18:19], s[88:89] op_sel_hi:[1,0]
	v_cvt_pk_bf16_f32 v16, v16, v17
	v_cvt_pk_bf16_f32 v17, v18, v19
	v_lshlrev_b32_e32 v18, 16, v37
	v_and_b32_e32 v19, 0xffff0000, v37
	v_pk_mul_f32 v[18:19], v[18:19], s[88:89] op_sel_hi:[1,0]
	v_lshlrev_b32_e32 v24, 16, v35
	v_cvt_pk_bf16_f32 v21, v18, v19
	v_lshlrev_b32_e32 v18, 16, v34
	v_and_b32_e32 v19, 0xffff0000, v34
	v_and_b32_e32 v25, 0xffff0000, v35
	v_pk_mul_f32 v[18:19], v[18:19], s[88:89] op_sel_hi:[1,0]
	v_pk_mul_f32 v[24:25], v[24:25], s[88:89] op_sel_hi:[1,0]
	v_cvt_pk_bf16_f32 v18, v18, v19
	v_lshlrev_b32_e32 v22, 16, v38
	v_and_b32_e32 v23, 0xffff0000, v38
	v_cvt_pk_bf16_f32 v19, v24, v25
	v_lshlrev_b32_e32 v24, 16, v39
	v_and_b32_e32 v25, 0xffff0000, v39
	v_pk_mul_f32 v[22:23], v[22:23], s[88:89] op_sel_hi:[1,0]
	v_pk_mul_f32 v[24:25], v[24:25], s[88:89] op_sel_hi:[1,0]
	v_cvt_pk_bf16_f32 v22, v22, v23
	v_cvt_pk_bf16_f32 v23, v24, v25
	v_mov_b32_e32 v24, 0xff800000
	s_and_saveexec_b64 s[4:5], s[2:3]
	s_cbranch_execz .LBB0_1046
	ds_read_b128 v[24:27], v197
	ds_read_b128 v[28:31], v197 offset:64
	s_waitcnt lgkmcnt(1)
	v_mfma_f32_16x16x32_bf16 v[24:27], v[24:27], v[16:19], 0
	s_waitcnt lgkmcnt(0)
	v_mfma_f32_16x16x32_bf16 v[24:27], v[28:31], v[20:23], v[24:27]
	s_nop 7
	v_pk_add_f32 v[68:69], v[80:81], v[24:25]
	v_pk_add_f32 v[70:71], v[82:83], v[26:27]
	v_max_f32_e32 v24, v68, v69
	v_max_f32_e32 v25, v70, v71
	v_max3_f32 v24, v24, v25, s68

	.amdhsa_kernel _Z4mega6Paramsii
		.amdhsa_group_segment_fixed_size 240
		.amdhsa_private_segment_fixed_size 0
		.amdhsa_kernarg_size 488
		.amdhsa_user_sgpr_count 2
		.amdhsa_user_sgpr_dispatch_ptr 0
		.amdhsa_user_sgpr_queue_ptr 0
		.amdhsa_user_sgpr_kernarg_segment_ptr 1
		.amdhsa_user_sgpr_dispatch_id 0
		.amdhsa_user_sgpr_kernarg_preload_length 0
		.amdhsa_user_sgpr_kernarg_preload_offset 0
		.amdhsa_user_sgpr_private_segment_size 0
		.amdhsa_uses_dynamic_stack 0
		.amdhsa_enable_private_segment 0
		.amdhsa_system_sgpr_workgroup_id_x 1
		.amdhsa_system_sgpr_workgroup_id_y 0
		.amdhsa_system_sgpr_workgroup_id_z 0
		.amdhsa_system_sgpr_workgroup_info 0
		.amdhsa_system_vgpr_workitem_id 2
		.amdhsa_next_free_vgpr 256
		.amdhsa_next_free_sgpr 102
		.amdhsa_accum_offset 256
		.amdhsa_reserve_vcc 1
		.amdhsa_float_round_mode_32 0
		.amdhsa_float_round_mode_16_64 0
		.amdhsa_float_denorm_mode_32 3
		.amdhsa_float_denorm_mode_16_64 3
		.amdhsa_dx10_clamp 1
		.amdhsa_ieee_mode 1
		.amdhsa_fp16_overflow 0
		.amdhsa_tg_split 0
		.amdhsa_exception_fp_ieee_invalid_op 0
		.amdhsa_exception_fp_denorm_src 0
		.amdhsa_exception_fp_ieee_div_zero 0
		.amdhsa_exception_fp_ieee_overflow 0
		.amdhsa_exception_fp_ieee_underflow 0
		.amdhsa_exception_fp_ieee_inexact 0
		.amdhsa_exception_int_div_zero 0
	.end_amdhsa_kernel

.Lfunc_end0:
	.size	_Z4mega6Paramsii, .Lfunc_end0-_Z4mega6Paramsii
	.set _Z4mega6Paramsii.num_vgpr, 256
	.set _Z4mega6Paramsii.num_agpr, 0
	.set _Z4mega6Paramsii.numbered_sgpr, 102
	.set _Z4mega6Paramsii.num_named_barrier, 0
	.set _Z4mega6Paramsii.private_seg_size, 0
	.set _Z4mega6Paramsii.uses_vcc, 1
	.set _Z4mega6Paramsii.uses_flat_scratch, 0
	.set _Z4mega6Paramsii.has_dyn_sized_stack, 0
	.set _Z4mega6Paramsii.has_recursion, 0
	.set _Z4mega6Paramsii.has_indirect_call, 0

amdhsa.kernels:
  - .agpr_count:     0
    .args:
      - .offset:         0
        .size:           224
        .value_kind:     by_value
      - .offset:         224
        .size:           4
        .value_kind:     by_value
      - .offset:         228
        .size:           4
        .value_kind:     by_value
      - .offset:         232
        .size:           4
        .value_kind:     hidden_block_count_x
      - .offset:         236
        .size:           4
        .value_kind:     hidden_block_count_y
      - .offset:         240
        .size:           4
        .value_kind:     hidden_block_count_z
      - .offset:         244
        .size:           2
        .value_kind:     hidden_group_size_x
      - .offset:         246
        .size:           2
        .value_kind:     hidden_group_size_y
      - .offset:         248
        .size:           2
        .value_kind:     hidden_group_size_z
      - .offset:         250
        .size:           2
        .value_kind:     hidden_remainder_x
      - .offset:         252
        .size:           2
        .value_kind:     hidden_remainder_y
      - .offset:         254
        .size:           2
        .value_kind:     hidden_remainder_z
      - .offset:         272
        .size:           8
        .value_kind:     hidden_global_offset_x
      - .offset:         280
        .size:           8
        .value_kind:     hidden_global_offset_y
      - .offset:         288
        .size:           8
        .value_kind:     hidden_global_offset_z
      - .offset:         296
        .size:           2
        .value_kind:     hidden_grid_dims
      - .offset:         320
        .size:           8
        .value_kind:     hidden_multigrid_sync_arg
      - .offset:         352
        .size:           4
        .value_kind:     hidden_dynamic_lds_size
    .group_segment_fixed_size: 240
    .kernarg_segment_align: 8
    .kernarg_segment_size: 488
    .language:       OpenCL C
    .language_version:
      - 2
      - 0
    .max_flat_workgroup_size: 512
    .name:           _Z4mega6Paramsii
    .private_segment_fixed_size: 0
    .sgpr_count:     108
    .sgpr_spill_count: 47
    .symbol:         _Z4mega6Paramsii.kd
    .uniform_work_group_size: 1
    .uses_dynamic_stack: false
    .vgpr_count:     256
    .vgpr_spill_count: 0
    .wavefront_size: 64
